# prompt attention micro-levers on top of v12 (bit-identical): MLA running max taken over raw scores and scaled once (31 fewer VALU per tile); FoX QK^T counted LDS wait lgkmcnt(8) then lgkmcnt(0) after
# speedup vs baseline: 1.0074x; 1.0011x over previous
.LBB0_720:
	s_lshl_b32 s37, s89, 14
	v_add_u32_e32 v2, s37, v137
	v_add_u32_e32 v3, v2, v146
	ds_read_b128 v[70:73], v3
	ds_read_b128 v[74:77], v3 offset:8192
	v_add_u32_e32 v3, v2, v147
	ds_read_b128 v[160:163], v3
	ds_read_b128 v[164:167], v3 offset:8192
	v_add_u32_e32 v3, v2, v148
	ds_read_b128 v[168:171], v3
	ds_read_b128 v[172:175], v3 offset:8192
	v_add_u32_e32 v3, v2, v149
	ds_read_b128 v[176:179], v3
	ds_read_b128 v[180:183], v3 offset:8192
	v_add_u32_e32 v3, v2, v150
	ds_read_b128 v[184:187], v3
	ds_read_b128 v[188:191], v3 offset:8192
	v_add_u32_e32 v3, v2, v151
	ds_read_b128 v[192:195], v3
	ds_read_b128 v[196:199], v3 offset:8192
	v_add_u32_e32 v3, v2, v152
	v_add_u32_e32 v2, v2, v153
	ds_read_b128 v[200:203], v3
	ds_read_b128 v[204:207], v3 offset:8192
	ds_read_b128 v[208:211], v2
	ds_read_b128 v[216:219], v2 offset:8192
	s_waitcnt lgkmcnt(8)
	v_mfma_f32_32x32x16_bf16 v[86:101], v[70:73], v[102:105], 0
	v_mfma_f32_32x32x16_bf16 v[70:85], v[74:77], v[102:105], 0
	v_mfma_f32_32x32x16_bf16 v[86:101], v[160:163], v[106:109], v[86:101]
	v_mfma_f32_32x32x16_bf16 v[70:85], v[164:167], v[106:109], v[70:85]
	v_mfma_f32_32x32x16_bf16 v[86:101], v[168:171], v[110:113], v[86:101]
	v_mfma_f32_32x32x16_bf16 v[70:85], v[172:175], v[110:113], v[70:85]
	v_mfma_f32_32x32x16_bf16 v[86:101], v[176:179], v[114:117], v[86:101]
	v_mfma_f32_32x32x16_bf16 v[70:85], v[180:183], v[114:117], v[70:85]
	s_waitcnt lgkmcnt(0)
	v_mfma_f32_32x32x16_bf16 v[86:101], v[184:187], v[118:121], v[86:101]
	v_mfma_f32_32x32x16_bf16 v[70:85], v[188:191], v[118:121], v[70:85]
	v_mfma_f32_32x32x16_bf16 v[86:101], v[192:195], v[122:125], v[86:101]
	v_mfma_f32_32x32x16_bf16 v[70:85], v[196:199], v[122:125], v[70:85]
	v_mfma_f32_32x32x16_bf16 v[86:101], v[200:203], v[126:129], v[86:101]
	v_mfma_f32_32x32x16_bf16 v[70:85], v[204:207], v[126:129], v[70:85]
	v_mfma_f32_32x32x16_bf16 v[86:101], v[208:211], v[130:133], v[86:101]
	v_mfma_f32_32x32x16_bf16 v[70:85], v[216:219], v[130:133], v[70:85]
	v_add_u32_e32 v2, s70, v155
	v_add_u32_e32 v3, 0x1e000, v2
	v_add_u32_e32 v5, 0x1e080, v2
	ds_read_b128 v[160:163], v3
	ds_read_b128 v[164:167], v5
	v_add_u32_e32 v3, 0x1e020, v2
	v_add_u32_e32 v5, 0x1e0a0, v2
	ds_read_b128 v[168:171], v3
	ds_read_b128 v[172:175], v5
	v_add_u32_e32 v3, 0x1e040, v2
	v_add_u32_e32 v5, 0x1e0c0, v2
	ds_read_b128 v[176:179], v3
	ds_read_b128 v[180:183], v5
	v_add_u32_e32 v3, 0x1e060, v2
	v_add_u32_e32 v2, 0x1e0e0, v2
	ds_read_b128 v[184:187], v3
	ds_read_b128 v[188:191], v2
	s_waitcnt lgkmcnt(0)
	v_fma_f32 v2, v100, s86, -v186
	v_fma_f32 v3, v101, s86, -v187
	v_fma_f32 v88, v88, s86, -v162
	v_fma_f32 v89, v89, s86, -v163
	v_fma_f32 v86, v86, s86, -v160
	v_fma_f32 v87, v87, s86, -v161
	v_fma_f32 v98, v98, s86, -v184
	v_fma_f32 v99, v99, s86, -v185
	v_fma_f32 v96, v96, s86, -v178
	v_fma_f32 v97, v97, s86, -v179
	v_fma_f32 v94, v94, s86, -v176
	v_fma_f32 v95, v95, s86, -v177
	v_fma_f32 v92, v92, s86, -v170
	v_fma_f32 v93, v93, s86, -v171
	v_fma_f32 v90, v90, s86, -v168
	v_fma_f32 v91, v91, s86, -v169
	v_fma_f32 v84, v84, s86, -v190
	v_fma_f32 v85, v85, s86, -v191
	v_fma_f32 v82, v82, s86, -v188
	v_fma_f32 v83, v83, s86, -v189
	v_fma_f32 v80, v80, s86, -v182
	v_fma_f32 v81, v81, s86, -v183
	v_fma_f32 v78, v78, s86, -v180
	v_fma_f32 v79, v79, s86, -v181
	v_fma_f32 v76, v76, s86, -v174
	v_fma_f32 v77, v77, s86, -v175
	v_fma_f32 v74, v74, s86, -v172
	v_fma_f32 v75, v75, s86, -v173
	v_fma_f32 v72, v72, s86, -v166
	v_fma_f32 v73, v73, s86, -v167
	s_cmp_le_i32 s85, s95
	v_fma_f32 v70, v70, s86, -v164
	v_fma_f32 v71, v71, s86, -v165
	s_cbranch_scc1 .LBB0_722
	v_cmp_gt_i32_e64 s[66:67], 26, v156
	v_cmp_gt_i32_e64 s[68:69], 27, v156
	v_cmp_gt_i32_e64 s[64:65], 25, v156
	s_and_b64 s[66:67], s[68:69], s[66:67]
	v_cmp_gt_i32_e64 s[62:63], 24, v156
	s_and_b64 s[64:65], s[66:67], s[64:65]
	v_cmp_gt_i32_e64 s[60:61], 19, v156
	s_and_b64 s[62:63], s[64:65], s[62:63]
	v_cmp_gt_i32_e64 s[58:59], 18, v156
	s_and_b64 s[60:61], s[62:63], s[60:61]
	v_cmp_gt_i32_e64 s[56:57], 17, v156
	s_and_b64 s[58:59], s[60:61], s[58:59]
	v_cmp_gt_i32_e64 s[54:55], 16, v156
	s_and_b64 s[56:57], s[58:59], s[56:57]
	v_cmp_gt_i32_e64 s[52:53], 11, v156
	s_and_b64 s[54:55], s[56:57], s[54:55]
	v_cmp_gt_i32_e64 s[50:51], 10, v156
	s_and_b64 s[52:53], s[54:55], s[52:53]
	v_cmp_gt_i32_e64 s[48:49], 9, v156
	s_and_b64 s[50:51], s[52:53], s[50:51]
	v_cmp_gt_i32_e64 s[46:47], 8, v156
	s_and_b64 s[48:49], s[50:51], s[48:49]
	v_cmp_gt_i32_e64 s[44:45], 3, v156
	s_and_b64 s[46:47], s[48:49], s[46:47]
	v_cmp_gt_i32_e64 s[42:43], 2, v156
	s_and_b64 s[44:45], s[46:47], s[44:45]
	v_cmp_gt_i32_e64 s[40:41], 1, v156
	s_and_b64 s[42:43], s[44:45], s[42:43]
	v_cmp_gt_i32_e64 s[0:1], 0, v156
	s_and_b64 s[40:41], s[42:43], s[40:41]
	s_and_b64 s[0:1], s[40:41], s[0:1]
	v_cmp_gt_i32_e64 s[34:35], 58, v156
	v_cndmask_b32_e64 v86, v86, v247, s[0:1]
	v_cmp_gt_i32_e64 s[0:1], 59, v156
	v_cmp_gt_i32_e64 s[30:31], 57, v156
	v_cmp_gt_i32_e64 s[28:29], 56, v156
	v_cndmask_b32_e64 v85, v85, v247, s[0:1]
	s_and_b64 s[0:1], s[0:1], s[34:35]
	v_cndmask_b32_e64 v84, v84, v247, s[0:1]
	s_and_b64 s[0:1], s[0:1], s[30:31]
	v_cmp_gt_i32_e64 s[26:27], 51, v156
	v_cndmask_b32_e64 v83, v83, v247, s[0:1]
	s_and_b64 s[0:1], s[0:1], s[28:29]
	v_cmp_gt_i32_e64 s[24:25], 50, v156
	v_cndmask_b32_e64 v82, v82, v247, s[0:1]
	s_and_b64 s[0:1], s[0:1], s[26:27]
	v_cmp_gt_i32_e64 s[22:23], 49, v156
	v_cndmask_b32_e64 v81, v81, v247, s[0:1]
	s_and_b64 s[0:1], s[0:1], s[24:25]
	v_cmp_gt_i32_e64 s[20:21], 48, v156
	v_cndmask_b32_e64 v80, v80, v247, s[0:1]
	s_and_b64 s[0:1], s[0:1], s[22:23]
	v_cmp_gt_i32_e64 s[18:19], 43, v156
	v_cndmask_b32_e64 v79, v79, v247, s[0:1]
	s_and_b64 s[0:1], s[0:1], s[20:21]
	v_cmp_gt_i32_e64 s[16:17], 42, v156
	v_cndmask_b32_e64 v78, v78, v247, s[0:1]
	s_and_b64 s[0:1], s[0:1], s[18:19]
	v_cmp_gt_i32_e64 s[14:15], 41, v156
	v_cndmask_b32_e64 v77, v77, v247, s[0:1]
	s_and_b64 s[0:1], s[0:1], s[16:17]
	v_cmp_gt_i32_e64 s[12:13], 40, v156
	v_cndmask_b32_e64 v76, v76, v247, s[0:1]
	s_and_b64 s[0:1], s[0:1], s[14:15]
	v_cmp_gt_i32_e64 s[10:11], 35, v156
	v_cndmask_b32_e64 v75, v75, v247, s[0:1]
	s_and_b64 s[0:1], s[0:1], s[12:13]
	v_cmp_gt_i32_e64 s[8:9], 34, v156
	v_cndmask_b32_e64 v74, v74, v247, s[0:1]
	s_and_b64 s[0:1], s[0:1], s[10:11]
	v_cmp_gt_i32_e64 s[6:7], 33, v156
	v_cndmask_b32_e64 v73, v73, v247, s[0:1]
	s_and_b64 s[0:1], s[0:1], s[8:9]
	v_cmp_gt_i32_e32 vcc, 32, v156
	v_cndmask_b32_e64 v72, v72, v247, s[0:1]
	s_and_b64 s[0:1], s[0:1], s[6:7]
	s_and_b64 vcc, s[0:1], vcc
	v_cndmask_b32_e64 v3, v3, v247, s[68:69]
	v_cndmask_b32_e64 v2, v2, v247, s[66:67]
	v_cndmask_b32_e64 v99, v99, v247, s[64:65]
	v_cndmask_b32_e64 v98, v98, v247, s[62:63]
	v_cndmask_b32_e64 v97, v97, v247, s[60:61]
	v_cndmask_b32_e64 v96, v96, v247, s[58:59]
	v_cndmask_b32_e64 v95, v95, v247, s[56:57]
	v_cndmask_b32_e64 v94, v94, v247, s[54:55]
	v_cndmask_b32_e64 v93, v93, v247, s[52:53]
	v_cndmask_b32_e64 v92, v92, v247, s[50:51]
	s_mov_b32 s51, 0x40c000
	v_cndmask_b32_e64 v91, v91, v247, s[48:49]
	s_mov_b64 s[48:49], 0x7ffff
	v_cndmask_b32_e64 v90, v90, v247, s[46:47]
	s_mov_b32 s47, 0x120000
	v_cndmask_b32_e64 v89, v89, v247, s[44:45]
	v_cndmask_b32_e64 v88, v88, v247, s[42:43]
	v_cndmask_b32_e64 v87, v87, v247, s[40:41]
	s_mov_b32 s40, 0x41000000
	v_cndmask_b32_e64 v71, v71, v247, s[0:1]
	v_cndmask_b32_e32 v70, v70, v247, vcc

.LBB0_749:
	s_mul_i32 s18, s28, 0x6000
	v_add_u32_e32 v2, s18, v1
	v_add_u32_e32 v3, v2, v159
	ds_read_b128 v[70:73], v3
	ds_read_b128 v[74:77], v3 offset:12288
	v_add_u32_e32 v3, v2, v170
	ds_read_b128 v[184:187], v3
	ds_read_b128 v[188:191], v3 offset:12288
	v_add_u32_e32 v3, v2, v171
	ds_read_b128 v[192:195], v3
	ds_read_b128 v[196:199], v3 offset:12288
	v_add_u32_e32 v3, v2, v172
	ds_read_b128 v[200:203], v3
	ds_read_b128 v[204:207], v3 offset:12288
	v_add_u32_e32 v3, v2, v173
	ds_read_b128 v[208:211], v3
	ds_read_b128 v[216:219], v3 offset:12288
	v_add_u32_e32 v3, v2, v174
	ds_read_b128 v[220:223], v3
	ds_read_b128 v[224:227], v3 offset:12288
	s_waitcnt lgkmcnt(0)
	v_mfma_f32_32x32x16_bf16 v[86:101], v[70:73], v[102:105], 0
	v_add_u32_e32 v3, v2, v175
	v_mfma_f32_32x32x16_bf16 v[70:85], v[74:77], v[102:105], 0
	v_mfma_f32_32x32x16_bf16 v[86:101], v[184:187], v[106:109], v[86:101]
	v_mfma_f32_32x32x16_bf16 v[70:85], v[188:191], v[106:109], v[70:85]
	ds_read_b128 v[184:187], v3
	ds_read_b128 v[188:191], v3 offset:12288
	v_add_u32_e32 v3, v2, v176
	v_mfma_f32_32x32x16_bf16 v[86:101], v[192:195], v[110:113], v[86:101]
	ds_read_b128 v[192:195], v3
	ds_read_b128 v[228:231], v3 offset:12288
	v_add_u32_e32 v3, v2, v177
	ds_read_b128 v[232:235], v3
	ds_read_b128 v[236:239], v3 offset:12288
	v_mfma_f32_32x32x16_bf16 v[70:85], v[196:199], v[110:113], v[70:85]
	v_mfma_f32_32x32x16_bf16 v[86:101], v[200:203], v[114:117], v[86:101]
	v_add_u32_e32 v3, v2, v178
	ds_read_b128 v[196:199], v3
	ds_read_b128 v[200:203], v3 offset:12288
	v_add_u32_e32 v3, v2, v179
	v_add_u32_e32 v2, v2, v180
	v_mfma_f32_32x32x16_bf16 v[70:85], v[204:207], v[114:117], v[70:85]
	v_mfma_f32_32x32x16_bf16 v[86:101], v[208:211], v[118:121], v[86:101]
	ds_read_b128 v[204:207], v3
	ds_read_b128 v[208:211], v3 offset:12288
	v_mfma_f32_32x32x16_bf16 v[70:85], v[216:219], v[118:121], v[70:85]
	v_mfma_f32_32x32x16_bf16 v[86:101], v[220:223], v[122:125], v[86:101]
	ds_read_b128 v[216:219], v2
	ds_read_b128 v[220:223], v2 offset:12288
	v_mfma_f32_32x32x16_bf16 v[70:85], v[224:227], v[122:125], v[70:85]
	s_waitcnt lgkmcnt(0)
	v_mfma_f32_32x32x16_bf16 v[86:101], v[184:187], v[126:129], v[86:101]
	v_mfma_f32_32x32x16_bf16 v[70:85], v[188:191], v[126:129], v[70:85]
	v_mfma_f32_32x32x16_bf16 v[86:101], v[192:195], v[130:133], v[86:101]
	v_mfma_f32_32x32x16_bf16 v[70:85], v[228:231], v[130:133], v[70:85]
	v_mfma_f32_32x32x16_bf16 v[86:101], v[232:235], v[134:137], v[86:101]
	v_mfma_f32_32x32x16_bf16 v[70:85], v[236:239], v[134:137], v[70:85]
	v_mfma_f32_32x32x16_bf16 v[86:101], v[196:199], v[138:141], v[86:101]
	v_mfma_f32_32x32x16_bf16 v[70:85], v[200:203], v[138:141], v[70:85]
	v_mfma_f32_32x32x16_bf16 v[86:101], v[204:207], v[142:145], v[86:101]
	v_mfma_f32_32x32x16_bf16 v[70:85], v[208:211], v[142:145], v[70:85]
	v_mfma_f32_32x32x16_bf16 v[86:101], v[216:219], v[146:149], v[86:101]
	v_mfma_f32_32x32x16_bf16 v[70:85], v[220:223], v[146:149], v[70:85]
	s_nop 10
	v_max_f32_e32 v2, v86, v87
	v_max3_f32 v2, v2, v88, v89
	v_max3_f32 v2, v2, v90, v91
	v_max3_f32 v2, v2, v92, v93
	v_max3_f32 v2, v2, v94, v95
	v_max3_f32 v2, v2, v96, v97
	v_max3_f32 v2, v2, v98, v99
	v_max3_f32 v2, v2, v100, v101
	v_max3_f32 v2, v2, v70, v71
	v_max3_f32 v2, v2, v72, v73
	v_max3_f32 v2, v2, v74, v75
	v_max3_f32 v2, v2, v76, v77
	v_max3_f32 v2, v2, v78, v79
	v_max3_f32 v2, v2, v80, v81
	v_max3_f32 v2, v2, v82, v83
	v_max3_f32 v2, v2, v84, v85
	v_mul_f32_e32 v2, 0x3dd53b94, v2
	v_mov_b32_e32 v3, v2
	s_nop 1
	v_permlane32_swap_b32_e32 v2, v3
	v_max_f32_e32 v3, v3, v3
	v_max_f32_e32 v2, v2, v2
	v_max_f32_e32 v2, v2, v3
	v_sub_f32_e32 v3, v2, v182
	v_cmp_ge_f32_e32 vcc, s40, v3
	s_cmp_eq_u64 vcc, exec
	v_max_f32_e32 v3, v182, v182
	v_max_f32_e32 v2, v3, v2
	s_cselect_b64 vcc, -1, 0
	v_sub_f32_e32 v184, v182, v2
	v_cndmask_b32_e32 v182, v2, v182, vcc
	v_fma_f32 v2, v86, s90, -v182
	v_exp_f32_e32 v86, v2
	v_fma_f32 v2, v70, s90, -v182
	v_exp_f32_e32 v3, v2
	v_fma_f32 v2, v87, s90, -v182
	v_exp_f32_e32 v87, v2
	v_fma_f32 v2, v71, s90, -v182
	v_add_f32_e32 v70, v3, v86
	v_exp_f32_e32 v5, v2
	v_exp_f32_e32 v2, v184
	v_add_f32_e32 v184, 0, v70
	v_fma_f32 v70, v88, s90, -v182
	v_exp_f32_e32 v88, v70
	v_fma_f32 v70, v72, s90, -v182
	v_exp_f32_e32 v70, v70
	v_add_f32_e32 v185, v5, v87
	v_fma_f32 v71, v89, s90, -v182
	v_exp_f32_e32 v89, v71
	v_fma_f32 v71, v73, s90, -v182
	v_add_f32_e32 v72, v185, v184
	v_add_f32_e32 v73, v70, v88
	v_add_f32_e32 v184, v73, v72
	v_fma_f32 v72, v90, s90, -v182
	v_exp_f32_e32 v71, v71
	v_exp_f32_e32 v90, v72
	v_fma_f32 v72, v74, s90, -v182
	v_exp_f32_e32 v72, v72
	v_add_f32_e32 v185, v71, v89
	v_fma_f32 v73, v91, s90, -v182
	v_exp_f32_e32 v91, v73
	v_fma_f32 v73, v75, s90, -v182
	v_add_f32_e32 v74, v185, v184
	v_add_f32_e32 v75, v72, v90
	v_add_f32_e32 v75, v75, v74
	v_fma_f32 v74, v92, s90, -v182
	v_exp_f32_e32 v73, v73
	v_exp_f32_e32 v92, v74
	v_fma_f32 v74, v76, s90, -v182
	v_exp_f32_e32 v74, v74
	v_add_f32_e32 v185, v73, v91
	v_fma_f32 v76, v93, s90, -v182
	v_exp_f32_e32 v184, v76
	v_fma_f32 v76, v77, s90, -v182
	v_add_f32_e32 v75, v185, v75
	v_add_f32_e32 v77, v74, v92
	v_add_f32_e32 v185, v77, v75
	v_fma_f32 v75, v94, s90, -v182
	v_exp_f32_e32 v76, v76
	v_exp_f32_e32 v93, v75
	v_fma_f32 v75, v78, s90, -v182
	v_exp_f32_e32 v75, v75
	v_add_f32_e32 v186, v76, v184
	v_fma_f32 v77, v95, s90, -v182
	v_exp_f32_e32 v94, v77
	v_fma_f32 v77, v79, s90, -v182
	v_add_f32_e32 v78, v186, v185
	v_add_f32_e32 v79, v75, v93
	v_add_f32_e32 v185, v79, v78
	v_fma_f32 v78, v96, s90, -v182
	v_exp_f32_e32 v77, v77
	v_exp_f32_e32 v95, v78
	v_fma_f32 v78, v80, s90, -v182
	v_exp_f32_e32 v78, v78
	v_add_f32_e32 v186, v77, v94
	v_fma_f32 v79, v97, s90, -v182
	v_exp_f32_e32 v96, v79
	v_fma_f32 v79, v81, s90, -v182
	v_add_f32_e32 v80, v186, v185
	v_add_f32_e32 v81, v78, v95
	v_add_f32_e32 v185, v81, v80
	v_fma_f32 v80, v98, s90, -v182
	v_exp_f32_e32 v79, v79
	v_exp_f32_e32 v97, v80
	v_fma_f32 v80, v82, s90, -v182
	v_exp_f32_e32 v80, v80
	v_add_f32_e32 v186, v79, v96
	v_fma_f32 v81, v99, s90, -v182
	v_exp_f32_e32 v98, v81
	v_fma_f32 v81, v83, s90, -v182
	v_add_f32_e32 v82, v186, v185
	v_add_f32_e32 v83, v80, v97
	v_add_f32_e32 v185, v83, v82
	v_fma_f32 v82, v100, s90, -v182
	v_exp_f32_e32 v81, v81
	v_exp_f32_e32 v99, v82
	v_fma_f32 v82, v84, s90, -v182
	v_fma_f32 v83, v101, s90, -v182
	v_exp_f32_e32 v82, v82
	v_exp_f32_e32 v84, v83
	v_fma_f32 v83, v85, s90, -v182
	v_exp_f32_e32 v83, v83
	v_add_f32_e32 v186, v81, v98
	v_add_f32_e32 v85, v186, v185
	v_add_f32_e32 v100, v82, v99
	v_add_f32_e32 v85, v100, v85
	v_add_f32_e32 v100, v83, v84
	v_add_f32_e32 v85, v100, v85
	v_cndmask_b32_e64 v2, v2, 1.0, vcc
	v_mov_b32_e32 v100, v85
	s_nop 1
	v_permlane32_swap_b32_e32 v85, v100
	v_cmp_gt_f32_e32 vcc, 1.0, v2
	s_cbranch_vccz .LBB0_751
	v_pk_mul_f32 v[68:69], v[68:69], v[2:3] op_sel_hi:[1,0]
	v_pk_mul_f32 v[66:67], v[66:67], v[2:3] op_sel_hi:[1,0]
	v_pk_mul_f32 v[64:65], v[64:65], v[2:3] op_sel_hi:[1,0]
	v_pk_mul_f32 v[62:63], v[62:63], v[2:3] op_sel_hi:[1,0]
	v_pk_mul_f32 v[60:61], v[60:61], v[2:3] op_sel_hi:[1,0]
	v_pk_mul_f32 v[58:59], v[58:59], v[2:3] op_sel_hi:[1,0]
	v_pk_mul_f32 v[56:57], v[56:57], v[2:3] op_sel_hi:[1,0]
	v_pk_mul_f32 v[54:55], v[54:55], v[2:3] op_sel_hi:[1,0]
	v_pk_mul_f32 v[52:53], v[52:53], v[2:3] op_sel_hi:[1,0]
	v_pk_mul_f32 v[50:51], v[50:51], v[2:3] op_sel_hi:[1,0]
	v_pk_mul_f32 v[48:49], v[48:49], v[2:3] op_sel_hi:[1,0]
	v_pk_mul_f32 v[46:47], v[46:47], v[2:3] op_sel_hi:[1,0]
	v_pk_mul_f32 v[44:45], v[44:45], v[2:3] op_sel_hi:[1,0]
	v_pk_mul_f32 v[42:43], v[42:43], v[2:3] op_sel_hi:[1,0]
	v_pk_mul_f32 v[40:41], v[40:41], v[2:3] op_sel_hi:[1,0]
	v_pk_mul_f32 v[38:39], v[38:39], v[2:3] op_sel_hi:[1,0]
	v_pk_mul_f32 v[36:37], v[36:37], v[2:3] op_sel_hi:[1,0]
	v_pk_mul_f32 v[34:35], v[34:35], v[2:3] op_sel_hi:[1,0]
	v_pk_mul_f32 v[32:33], v[32:33], v[2:3] op_sel_hi:[1,0]
	v_pk_mul_f32 v[30:31], v[30:31], v[2:3] op_sel_hi:[1,0]
	v_pk_mul_f32 v[28:29], v[28:29], v[2:3] op_sel_hi:[1,0]
	v_pk_mul_f32 v[26:27], v[26:27], v[2:3] op_sel_hi:[1,0]
	v_pk_mul_f32 v[24:25], v[24:25], v[2:3] op_sel_hi:[1,0]
	v_pk_mul_f32 v[22:23], v[22:23], v[2:3] op_sel_hi:[1,0]
	v_pk_mul_f32 v[20:21], v[20:21], v[2:3] op_sel_hi:[1,0]
	v_pk_mul_f32 v[18:19], v[18:19], v[2:3] op_sel_hi:[1,0]
	v_pk_mul_f32 v[16:17], v[16:17], v[2:3] op_sel_hi:[1,0]
	v_pk_mul_f32 v[14:15], v[14:15], v[2:3] op_sel_hi:[1,0]
	v_pk_mul_f32 v[12:13], v[12:13], v[2:3] op_sel_hi:[1,0]
	v_pk_mul_f32 v[10:11], v[10:11], v[2:3] op_sel_hi:[1,0]
	v_pk_mul_f32 v[8:9], v[8:9], v[2:3] op_sel_hi:[1,0]
	v_pk_mul_f32 v[6:7], v[6:7], v[2:3] op_sel_hi:[1,0]
